# v53 with the SSM hoist fixed: vmcnt(0) now precedes the first read of the hoisted parameter loads (the earlier version copied them before the wait, a latent race)
# speedup vs baseline: 1.0076x; 1.0005x over previous
; __device__ void phase_ssm(int j, unsigned char* lds) {
;     ...
;           for (int i = tid; i < NS * NP; i += NTHREADS) { const int n = i >> 4; const f32x4 t4 = TMP[n]; const size_t o = ((size_t)j * NG + g) * NS * NP + i;
;               const float bre = pq->in[11][o], bim = pq->in[12][o]; BBAR[n * 17 + (i & 15)] = (f32x2){t4[2] * bre - t4[3] * bim, t4[2] * bim + t4[3] * bre}; }
;           for (int i = tid; i < NP * NS; i += NTHREADS) { const size_t o = ((size_t)j * NG + g) * NP * NS + i; CC[(i >> 6) * 65 + (i & 63)] = (f32x2){pq->in[13][o], pq->in[14][o]}; }
.LBB0_706:
	v_and_b32_e32 v8, -16, v0
	v_add_u32_e32 v9, 0, v8
	s_waitcnt vmcnt(0)
	v_mov_b32_e32 v8, v46
	v_mov_b32_e32 v10, v47
	ds_read_b64 v[12:13], v9 offset:46216
	v_ashrrev_i32_e32 v16, 4, v0
	v_cmp_lt_i32_e32 vcc, s33, v0
	s_or_b64 s[24:25], vcc, s[24:25]
	s_waitcnt vmcnt(0) lgkmcnt(0)
	v_pk_mul_f32 v[10:11], v[12:13], v[10:11] op_sel:[1,0] op_sel_hi:[0,0]
	v_pk_fma_f32 v[14:15], v[12:13], v[8:9], v[10:11] neg_lo:[0,0,1] neg_hi:[0,0,1]
	v_pk_fma_f32 v[8:9], v[12:13], v[8:9], v[10:11] op_sel_hi:[1,0,1]
	s_nop 0
	v_mov_b32_e32 v15, v9
	v_mad_u64_u32 v[8:9], s[34:35], v16, s23, v[144:145]
	ds_write_b64 v8, v[14:15] offset:8704
	v_add_u32_e32 v8, 0x200, v0
	v_mov_b32_e32 v0, v8
	s_andn2_b64 exec, exec, s[24:25]
	v_mov_b32_e32 v46, v48
	v_mov_b32_e32 v47, v49
	s_cbranch_execnz .LBB0_706
	s_or_b64 exec, exec, s[24:25]
	s_mov_b64 s[24:25], 0
	v_mov_b32_e32 v0, v134
	s_waitcnt lgkmcnt(0)
.LBB0_708:
	s_waitcnt vmcnt(0)
	v_mov_b32_e32 v6, v50
	v_mov_b32_e32 v7, v51
	v_ashrrev_i32_e32 v8, 6, v0
	v_mad_u64_u32 v[8:9], s[34:35], v8, s95, v[146:147]
	v_cmp_lt_i32_e32 vcc, s33, v0
	s_or_b64 s[24:25], vcc, s[24:25]
	s_waitcnt vmcnt(0)
	ds_write_b64 v8, v[6:7] offset:17408
	v_add_u32_e32 v6, 0x200, v0
	v_mov_b32_e32 v0, v6
	s_andn2_b64 exec, exec, s[24:25]
	v_mov_b32_e32 v50, v52
	v_mov_b32_e32 v51, v53
	s_cbranch_execnz .LBB0_708
